# attention loop: dropped the m0 save/restore SALU pairs around the 8 LDS-DMA issues per tile pair (no m0 consumer relies on the old value)
# speedup vs baseline: 1.0024x; 1.0024x over previous
; #define LAS __attribute__((address_space(3)))
; #define MFMA32(a, b, c) __builtin_amdgcn_mfma_f32_32x32x16_bf16((a), (b), (c), 0, 0, 0)
; DI void attn_unit(const bf16_t* Q, const bf16_t* Kp, const bf16_t* Vp, bf16_t* O, size_t qrow0, size_t krow0, int ntile, int h, float lam, float lam_init, const float* gsub, LAS unsigned char* lds) {
;     ...
;     for (int t = 0; t < ntile; t += 2) {
;       {
;         { const int tk = (t + 4 < ntile) ? t + 4 : ntile - 1; AT_ISSUE_K(tk, ks0); const int tv = (t + 2 < ntile) ? t + 2 : ntile - 1; AT_ISSUE_V(tv, vs1); }
;         LAS unsigned char* kb = lds + KRING + ks1 * SLOT + kro;
;         LAS unsigned char* vb = lds + VRING + vsm1 * SLOT + vro;
;         __builtin_amdgcn_s_setprio(1);
;         { bf16x8 ql[4];
; #pragma unroll
;           for (int d0 = 0; d0 < 4; ++d0) ql[d0] = qf[d0];
; #pragma unroll
;           for (int kh = 0; kh < 2; ++kh) {
;             bf16x8 kf[4];
; #pragma unroll
;             for (int e = 0; e < 4; ++e) kf[e] = *(const LAS bf16x8*)(kb + kh * 4096 + (((2 * e + hh) ^ ksw) * 16));
;             sn[kh] = MFMA32(kf[0], ql[0], negm);
; #pragma unroll
;             for (int d0 = 1; d0 < 4; ++d0) sn[kh] = MFMA32(kf[d0], ql[d0], sn[kh]);
;             __builtin_amdgcn_sched_barrier(0);
;           } }
; #pragma unroll
;         for (int j = 0; j < 4; ++j) {
;             s16x4 lo[4], hi[4];
; #pragma unroll
;             for (int e = 0; e < 4; ++e) { LAS unsigned char* vp = vb + j * 4096 + ((e ^ q4) * 64);
;                 lo[e] = __builtin_bit_cast(s16x4, __builtin_amdgcn_ds_read_tr16_b64_v4i16((LAS s16x4*)vp));
;                 hi[e] = __builtin_bit_cast(s16x4, __builtin_amdgcn_ds_read_tr16_b64_v4i16((LAS s16x4*)(vp + 2048))); }
; #pragma unroll
;             for (int e = 0; e < 4; ++e) ot[e] = MFMA32(__builtin_shufflevector(lo[e], hi[e], 0, 1, 2, 3, 4, 5, 6, 7), __builtin_bit_cast(bf16x8, pp[j]), ot[e]);
;             __builtin_amdgcn_sched_barrier(0);
;         }
;         __builtin_amdgcn_s_setprio(0);
;         if (!shifted) {
;             ps = 0.f;
; #pragma unroll
;             for (int kh = 0; kh < 2; ++kh)
; #pragma unroll
;                 for (int i = 0; i < 16; ++i) { sc[kh][i] = __builtin_amdgcn_exp2f(sc[kh][i]); ps += sc[kh][i]; }
;             l_run += ps;
;         }
.LBB0_573:
	s_lshl_b32 s80, s74, 14
	s_lshl_b32 s78, s70, 14
	s_setprio 1
	v_add_u32_e32 v1, s80, v200
	v_add_u32_e32 v226, v1, v201
	v_add_u32_e32 v207, v1, v202
	v_add_u32_e32 v221, v1, v203
	v_add_u32_e32 v1, v1, v204
	ds_read_b128 v[182:185], v226
	ds_read_b128 v[222:225], v207
	ds_read_b128 v[228:231], v221
	ds_read_b128 v[240:243], v1
	ds_read_b128 v[244:247], v226 offset:4096
	ds_read_b128 v[248:251], v207 offset:4096
	v_add_u32_e32 v227, s78, v219
	v_add_u32_e32 v226, v227, v218
	v_add_u32_e32 v207, v227, v217
	v_add_u32_e32 v235, v227, v216
	v_add_u32_e32 v227, v227, v214
	s_min_u32 s40, s76, 63
	s_add_i32 s40, s40, 4
	s_lshl_b32 s40, s40, 17
	s_add_u32 s40, s98, s40
	s_addc_u32 s41, s99, 0
	s_lshl_b32 s75, s77, 14
	s_add_i32 s92, s75, s68
	s_mov_b32 m0, s92
	s_nop 0
	global_load_lds_dwordx4 v252, s[40:41]
	s_add_u32 s40, s40, 0x80
	s_addc_u32 s41, s41, 0
	s_add_i32 s92, s75, s71
	s_mov_b32 m0, s92
	s_nop 0
	global_load_lds_dwordx4 v252, s[40:41]
	s_waitcnt lgkmcnt(5)
	v_mfma_f32_32x32x16_bf16 v[114:129], v[182:185], v[146:149], v[98:113]
	ds_read_b128 v[182:185], v221 offset:4096
	s_waitcnt lgkmcnt(5)
	v_mfma_f32_32x32x16_bf16 v[114:129], v[222:225], v[150:153], v[114:129]
	ds_read_b128 v[222:225], v1 offset:4096
	s_add_i32 s75, s76, 2
	s_min_u32 s40, s75, 0x43
	s_lshl_b32 s40, s40, 17
	s_add_u32 s40, s50, s40
	s_addc_u32 s41, s51, 0
	s_lshl_b32 s79, s69, 14
	s_add_i32 s77, s72, s79
	s_mov_b32 m0, s77
	s_nop 0
	global_load_lds_dwordx4 v194, s[40:41]
	s_waitcnt lgkmcnt(5)
	v_mfma_f32_32x32x16_bf16 v[114:129], v[228:231], v[154:157], v[114:129]
	ds_read_b64_tr_b16 v[228:229], v226
	ds_read_b64_tr_b16 v[230:231], v226 offset:2048
	s_waitcnt lgkmcnt(6)
	v_mfma_f32_32x32x16_bf16 v[114:129], v[240:243], v[158:161], v[114:129]
	ds_read_b64_tr_b16 v[240:241], v207
	ds_read_b64_tr_b16 v[242:243], v207 offset:2048
	s_add_i32 s77, s73, s79
	s_mov_b32 m0, s77
	s_nop 0
	global_load_lds_dwordx4 v196, s[40:41]
	s_waitcnt lgkmcnt(7)
	v_mfma_f32_32x32x16_bf16 v[130:145], v[244:247], v[146:149], v[98:113]
	ds_read_b64_tr_b16 v[244:245], v235
	ds_read_b64_tr_b16 v[246:247], v235 offset:2048
	s_waitcnt lgkmcnt(8)
	v_mfma_f32_32x32x16_bf16 v[130:145], v[248:251], v[150:153], v[130:145]
	ds_read_b64_tr_b16 v[248:249], v227
	ds_read_b64_tr_b16 v[250:251], v227 offset:2048
	s_waitcnt lgkmcnt(9)
	v_mfma_f32_32x32x16_bf16 v[130:145], v[182:185], v[154:157], v[130:145]
	ds_read_b64_tr_b16 v[182:183], v226 offset:4096
	ds_read_b64_tr_b16 v[184:185], v226 offset:6144
	s_waitcnt lgkmcnt(10)
	v_mfma_f32_32x32x16_bf16 v[130:145], v[222:225], v[158:161], v[130:145]
	ds_read_b64_tr_b16 v[222:223], v207 offset:4096
	ds_read_b64_tr_b16 v[224:225], v207 offset:6144
	s_waitcnt lgkmcnt(10)
	v_mfma_f32_32x32x16_bf16 v[50:65], v[228:231], v[174:177], v[50:65]
	ds_read_b64_tr_b16 v[228:229], v235 offset:4096
	ds_read_b64_tr_b16 v[230:231], v235 offset:6144
	s_waitcnt lgkmcnt(10)
	v_mfma_f32_32x32x16_bf16 v[34:49], v[240:243], v[174:177], v[34:49]
	ds_read_b64_tr_b16 v[240:241], v227 offset:4096
	ds_read_b64_tr_b16 v[242:243], v227 offset:6144
	s_waitcnt lgkmcnt(10)
	v_mfma_f32_32x32x16_bf16 v[18:33], v[244:247], v[174:177], v[18:33]
	ds_read_b64_tr_b16 v[244:245], v226 offset:8192
	ds_read_b64_tr_b16 v[246:247], v226 offset:10240
	s_waitcnt lgkmcnt(10)
	v_mfma_f32_32x32x16_bf16 v[2:17], v[248:251], v[174:177], v[2:17]
	ds_read_b64_tr_b16 v[248:249], v207 offset:8192
	ds_read_b64_tr_b16 v[250:251], v207 offset:10240
	s_waitcnt lgkmcnt(10)
	v_mfma_f32_32x32x16_bf16 v[50:65], v[182:185], v[170:173], v[50:65]
	ds_read_b64_tr_b16 v[182:183], v235 offset:8192
	ds_read_b64_tr_b16 v[184:185], v235 offset:10240
	s_waitcnt lgkmcnt(10)
	v_mfma_f32_32x32x16_bf16 v[34:49], v[222:225], v[170:173], v[34:49]
	ds_read_b64_tr_b16 v[222:223], v227 offset:8192
	ds_read_b64_tr_b16 v[224:225], v227 offset:10240
	s_waitcnt lgkmcnt(10)
	v_mfma_f32_32x32x16_bf16 v[18:33], v[228:231], v[170:173], v[18:33]
	ds_read_b64_tr_b16 v[228:229], v226 offset:12288
	ds_read_b64_tr_b16 v[230:231], v226 offset:14336
	s_waitcnt lgkmcnt(10)
	v_mfma_f32_32x32x16_bf16 v[2:17], v[240:243], v[170:173], v[2:17]
	ds_read_b64_tr_b16 v[240:241], v207 offset:12288
	ds_read_b64_tr_b16 v[242:243], v207 offset:14336
	s_waitcnt lgkmcnt(10)
	v_mfma_f32_32x32x16_bf16 v[50:65], v[244:247], v[166:169], v[50:65]
	ds_read_b64_tr_b16 v[244:245], v235 offset:12288
	ds_read_b64_tr_b16 v[246:247], v235 offset:14336
	s_waitcnt lgkmcnt(10)
	v_mfma_f32_32x32x16_bf16 v[34:49], v[248:251], v[166:169], v[34:49]
	ds_read_b64_tr_b16 v[248:249], v227 offset:12288
	ds_read_b64_tr_b16 v[250:251], v227 offset:14336
	s_waitcnt lgkmcnt(10)
	v_mfma_f32_32x32x16_bf16 v[18:33], v[182:185], v[166:169], v[18:33]
	s_waitcnt lgkmcnt(8)
	v_mfma_f32_32x32x16_bf16 v[2:17], v[222:225], v[166:169], v[2:17]
	s_waitcnt lgkmcnt(6)
	v_mfma_f32_32x32x16_bf16 v[50:65], v[228:231], v[162:165], v[50:65]
	s_waitcnt lgkmcnt(4)
	v_mfma_f32_32x32x16_bf16 v[34:49], v[240:243], v[162:165], v[34:49]
	s_waitcnt lgkmcnt(2)
	v_mfma_f32_32x32x16_bf16 v[18:33], v[244:247], v[162:165], v[18:33]
	s_waitcnt lgkmcnt(0)
	v_mfma_f32_32x32x16_bf16 v[2:17], v[248:251], v[162:165], v[2:17]
	s_setprio 0
	v_cndmask_b32_e64 v1, 0, 1, s[54:55]
	v_cmp_ne_u32_e64 s[40:41], 1, v1
	s_andn2_b64 vcc, exec, s[54:55]
	s_cbranch_vccnz .LBB0_575
	v_exp_f32_e32 v66, v66
	v_exp_f32_e32 v67, v67
	v_exp_f32_e32 v68, v68
	v_exp_f32_e32 v69, v69
	v_add_f32_e32 v1, 0, v66
	v_exp_f32_e32 v70, v70
	v_add_f32_e32 v1, v67, v1
	v_exp_f32_e32 v71, v71
	v_add_f32_e32 v1, v68, v1
	v_exp_f32_e32 v72, v72
	v_add_f32_e32 v1, v69, v1
	v_exp_f32_e32 v73, v73
	v_add_f32_e32 v1, v70, v1
	v_exp_f32_e32 v74, v74
	v_add_f32_e32 v1, v71, v1
	v_exp_f32_e32 v75, v75
	v_add_f32_e32 v1, v72, v1
	v_exp_f32_e32 v76, v76
	v_add_f32_e32 v1, v73, v1
	v_exp_f32_e32 v77, v77
	v_add_f32_e32 v1, v74, v1
	v_exp_f32_e32 v78, v78
	v_add_f32_e32 v1, v75, v1
	v_exp_f32_e32 v79, v79
	v_add_f32_e32 v1, v76, v1
	v_exp_f32_e32 v80, v80
	v_add_f32_e32 v1, v77, v1
	v_exp_f32_e32 v81, v81
	v_add_f32_e32 v1, v78, v1
	v_exp_f32_e32 v82, v82
	v_add_f32_e32 v1, v79, v1
	v_exp_f32_e32 v83, v83
	v_add_f32_e32 v1, v80, v1
	v_exp_f32_e32 v84, v84
	v_add_f32_e32 v1, v81, v1
	v_exp_f32_e32 v85, v85
	v_add_f32_e32 v1, v82, v1
	v_exp_f32_e32 v86, v86
	v_add_f32_e32 v1, v83, v1
	v_exp_f32_e32 v87, v87
	v_add_f32_e32 v1, v84, v1
	v_exp_f32_e32 v88, v88
	v_add_f32_e32 v1, v85, v1
	v_exp_f32_e32 v89, v89
	v_add_f32_e32 v1, v86, v1
	v_exp_f32_e32 v90, v90
	v_add_f32_e32 v1, v87, v1
	v_exp_f32_e32 v91, v91
	v_add_f32_e32 v1, v88, v1
	v_exp_f32_e32 v92, v92
	v_add_f32_e32 v1, v89, v1
	v_exp_f32_e32 v93, v93
	v_add_f32_e32 v1, v90, v1
	v_exp_f32_e32 v94, v94
	v_add_f32_e32 v1, v91, v1
	v_exp_f32_e32 v95, v95
	v_add_f32_e32 v1, v92, v1
	v_exp_f32_e32 v96, v96
	v_add_f32_e32 v1, v93, v1
	v_exp_f32_e32 v97, v97
	v_add_f32_e32 v1, v94, v1
	v_add_f32_e32 v1, v95, v1
	v_add_f32_e32 v1, v96, v1
	v_add_f32_e32 v220, v97, v1
	v_add_f32_e32 v213, v213, v220

; #define LAS __attribute__((address_space(3)))
; #define MFMA32(a, b, c) __builtin_amdgcn_mfma_f32_32x32x16_bf16((a), (b), (c), 0, 0, 0)
; DI void attn_unit(const bf16_t* Q, const bf16_t* Kp, const bf16_t* Vp, bf16_t* O, size_t qrow0, size_t krow0, int ntile, int h, float lam, float lam_init, const float* gsub, LAS unsigned char* lds) {
;     ...
;         for (int kh = 0; kh < 2; ++kh)
; #pragma unroll
;     ...
;       {
;         const int t1 = t + 1;
;         { const int tk = (t1 + 4 < ntile) ? t1 + 4 : ntile - 1; AT_ISSUE_K(tk, ks0); const int tv = (t1 + 2 < ntile) ? t1 + 2 : ntile - 1; AT_ISSUE_V(tv, vs1); }
;         LAS unsigned char* kb = lds + KRING + ks1 * SLOT + kro;
;         LAS unsigned char* vb = lds + VRING + vsm1 * SLOT + vro;
;         __builtin_amdgcn_s_setprio(1);
;         { bf16x8 ql[4];
; #pragma unroll
;           for (int d0 = 0; d0 < 4; ++d0) ql[d0] = qf[d0];
; #pragma unroll
;           for (int kh = 0; kh < 2; ++kh) {
;             bf16x8 kf[4];
; #pragma unroll
;             for (int e = 0; e < 4; ++e) kf[e] = *(const LAS bf16x8*)(kb + kh * 4096 + (((2 * e + hh) ^ ksw) * 16));
;             sc[kh] = MFMA32(kf[0], ql[0], negm);
; #pragma unroll
;             for (int d0 = 1; d0 < 4; ++d0) sc[kh] = MFMA32(kf[d0], ql[d0], sc[kh]);
;             __builtin_amdgcn_sched_barrier(0);
;           } }
; #pragma unroll
;         for (int j = 0; j < 4; ++j) {
;             s16x4 lo[4], hi[4];
; #pragma unroll
;             for (int e = 0; e < 4; ++e) { LAS unsigned char* vp = vb + j * 4096 + ((e ^ q4) * 64);
;                 lo[e] = __builtin_bit_cast(s16x4, __builtin_amdgcn_ds_read_tr16_b64_v4i16((LAS s16x4*)vp));
;                 hi[e] = __builtin_bit_cast(s16x4, __builtin_amdgcn_ds_read_tr16_b64_v4i16((LAS s16x4*)(vp + 2048))); }
; #pragma unroll
;             for (int e = 0; e < 4; ++e) ot[e] = MFMA32(__builtin_shufflevector(lo[e], hi[e], 0, 1, 2, 3, 4, 5, 6, 7), __builtin_bit_cast(bf16x8, pp[j]), ot[e]);
;             __builtin_amdgcn_sched_barrier(0);
;         }
;         __builtin_amdgcn_s_setprio(0);
;         if (!shifted) {
;             ps = 0.f;
; #pragma unroll
;             for (int kh = 0; kh < 2; ++kh)
; #pragma unroll
;                 for (int i = 0; i < 16; ++i) { sn[kh][i] = __builtin_amdgcn_exp2f(sn[kh][i]); ps += sn[kh][i]; }
;             l_run += ps;
;         }
.LBB0_579:
	s_add_i32 s77, s74, 1
	s_and_b32 s77, s77, 3
	s_addk_i32 s78, 0x4000
	s_and_b32 s78, s78, 0xc000
	s_setprio 1
	v_lshl_add_u32 v1, s77, 14, v200
	v_add_u32_e32 v226, v1, v201
	v_add_u32_e32 v207, v1, v202
	v_add_u32_e32 v221, v1, v203
	v_add_u32_e32 v1, v1, v204
	ds_read_b128 v[182:185], v226
	ds_read_b128 v[222:225], v207
	ds_read_b128 v[228:231], v221
	ds_read_b128 v[240:243], v1
	ds_read_b128 v[244:247], v226 offset:4096
	ds_read_b128 v[248:251], v207 offset:4096
	v_add_u32_e32 v227, s78, v219
	v_add_u32_e32 v226, v227, v218
	v_add_u32_e32 v207, v227, v217
	v_add_u32_e32 v235, v227, v216
	v_add_u32_e32 v227, v227, v214
	v_cvt_pk_bf16_f32 v170, v66, v67
	v_cvt_pk_bf16_f32 v171, v68, v69
	v_cvt_pk_bf16_f32 v172, v70, v71
	v_cvt_pk_bf16_f32 v173, v72, v73
	v_cvt_pk_bf16_f32 v174, v74, v75
	v_cvt_pk_bf16_f32 v175, v76, v77
	v_cvt_pk_bf16_f32 v176, v78, v79
	v_cvt_pk_bf16_f32 v177, v80, v81
	v_cvt_pk_bf16_f32 v166, v82, v83
	v_cvt_pk_bf16_f32 v167, v84, v85
	v_cvt_pk_bf16_f32 v168, v86, v87
	v_cvt_pk_bf16_f32 v169, v88, v89
	v_cvt_pk_bf16_f32 v162, v90, v91
	v_cvt_pk_bf16_f32 v163, v92, v93
	v_cvt_pk_bf16_f32 v164, v94, v95
	v_cvt_pk_bf16_f32 v165, v96, v97
	s_min_u32 s81, s76, 62
	s_add_i32 s81, s81, 5
	s_lshl_b32 s81, s81, 17
	s_add_u32 s82, s98, s81
	s_addc_u32 s83, s99, 0
	s_add_i32 s81, s80, s68
	s_mov_b32 m0, s81
	s_nop 0
	global_load_lds_dwordx4 v252, s[82:83]
	s_waitcnt lgkmcnt(5)
	v_mfma_f32_32x32x16_bf16 v[66:81], v[182:185], v[146:149], v[98:113]
	ds_read_b128 v[182:185], v221 offset:4096
	s_waitcnt lgkmcnt(5)
	v_mfma_f32_32x32x16_bf16 v[66:81], v[222:225], v[150:153], v[66:81]
	ds_read_b128 v[222:225], v1 offset:4096
	s_add_u32 s82, s82, 0x80
	s_addc_u32 s83, s83, 0
	s_add_i32 s81, s80, s71
	s_mov_b32 m0, s81
	s_nop 0
	global_load_lds_dwordx4 v252, s[82:83]
	s_waitcnt lgkmcnt(5)
	v_mfma_f32_32x32x16_bf16 v[66:81], v[228:231], v[154:157], v[66:81]
	ds_read_b64_tr_b16 v[228:229], v226
	ds_read_b64_tr_b16 v[230:231], v226 offset:2048
	s_waitcnt lgkmcnt(6)
	v_mfma_f32_32x32x16_bf16 v[66:81], v[240:243], v[158:161], v[66:81]
	ds_read_b64_tr_b16 v[240:241], v207
	ds_read_b64_tr_b16 v[242:243], v207 offset:2048
	s_min_u32 s80, s76, 64
	s_lshl_b32 s80, s80, 17
	s_add_u32 s80, s50, s80
	s_addc_u32 s81, s51, 0
	s_add_u32 s80, s80, 0x60000
	s_addc_u32 s81, s81, 0
	s_addk_i32 s79, 0x4000
	s_or_b32 s82, s79, 0x10000
	s_add_i32 s82, s82, s68
	s_or_b32 s79, s79, 0x12000
	s_mov_b32 m0, s82
	s_nop 0
	global_load_lds_dwordx4 v194, s[80:81]
	s_waitcnt lgkmcnt(7)
	v_mfma_f32_32x32x16_bf16 v[82:97], v[244:247], v[146:149], v[98:113]
	ds_read_b64_tr_b16 v[244:245], v235
	ds_read_b64_tr_b16 v[246:247], v235 offset:2048
	s_waitcnt lgkmcnt(8)
	v_mfma_f32_32x32x16_bf16 v[82:97], v[248:251], v[150:153], v[82:97]
	ds_read_b64_tr_b16 v[248:249], v227
	ds_read_b64_tr_b16 v[250:251], v227 offset:2048
	s_add_i32 s79, s79, s68
	s_mov_b32 m0, s79
	s_nop 0
	global_load_lds_dwordx4 v196, s[80:81]
	s_waitcnt lgkmcnt(9)
	v_mfma_f32_32x32x16_bf16 v[82:97], v[182:185], v[154:157], v[82:97]
	ds_read_b64_tr_b16 v[182:183], v226 offset:4096
	ds_read_b64_tr_b16 v[184:185], v226 offset:6144
	s_waitcnt lgkmcnt(10)
	v_mfma_f32_32x32x16_bf16 v[82:97], v[222:225], v[158:161], v[82:97]
	ds_read_b64_tr_b16 v[222:223], v207 offset:4096
	ds_read_b64_tr_b16 v[224:225], v207 offset:6144
	s_waitcnt lgkmcnt(10)
	v_mfma_f32_32x32x16_bf16 v[50:65], v[228:231], v[170:173], v[50:65]
	ds_read_b64_tr_b16 v[228:229], v235 offset:4096
	ds_read_b64_tr_b16 v[230:231], v235 offset:6144
	s_waitcnt lgkmcnt(10)
	v_mfma_f32_32x32x16_bf16 v[34:49], v[240:243], v[170:173], v[34:49]
	ds_read_b64_tr_b16 v[240:241], v227 offset:4096
	ds_read_b64_tr_b16 v[242:243], v227 offset:6144
	s_waitcnt lgkmcnt(10)
	v_mfma_f32_32x32x16_bf16 v[18:33], v[244:247], v[170:173], v[18:33]
	ds_read_b64_tr_b16 v[244:245], v226 offset:8192
	ds_read_b64_tr_b16 v[246:247], v226 offset:10240
	s_waitcnt lgkmcnt(10)
	v_mfma_f32_32x32x16_bf16 v[2:17], v[248:251], v[170:173], v[2:17]
	ds_read_b64_tr_b16 v[248:249], v207 offset:8192
	ds_read_b64_tr_b16 v[250:251], v207 offset:10240
	s_waitcnt lgkmcnt(10)
	v_mfma_f32_32x32x16_bf16 v[50:65], v[182:185], v[174:177], v[50:65]
	ds_read_b64_tr_b16 v[182:183], v235 offset:8192
	ds_read_b64_tr_b16 v[184:185], v235 offset:10240
	s_waitcnt lgkmcnt(10)
	v_mfma_f32_32x32x16_bf16 v[34:49], v[222:225], v[174:177], v[34:49]
	ds_read_b64_tr_b16 v[222:223], v227 offset:8192
	ds_read_b64_tr_b16 v[224:225], v227 offset:10240
	s_waitcnt lgkmcnt(10)
	v_mfma_f32_32x32x16_bf16 v[18:33], v[228:231], v[174:177], v[18:33]
	ds_read_b64_tr_b16 v[228:229], v226 offset:12288
	ds_read_b64_tr_b16 v[230:231], v226 offset:14336
	s_waitcnt lgkmcnt(10)
	v_mfma_f32_32x32x16_bf16 v[2:17], v[240:243], v[174:177], v[2:17]
	ds_read_b64_tr_b16 v[240:241], v207 offset:12288
	ds_read_b64_tr_b16 v[242:243], v207 offset:14336
	s_waitcnt lgkmcnt(10)
	v_mfma_f32_32x32x16_bf16 v[50:65], v[244:247], v[166:169], v[50:65]
	ds_read_b64_tr_b16 v[244:245], v235 offset:12288
	ds_read_b64_tr_b16 v[246:247], v235 offset:14336
	s_waitcnt lgkmcnt(10)
	v_mfma_f32_32x32x16_bf16 v[34:49], v[248:251], v[166:169], v[34:49]
	ds_read_b64_tr_b16 v[248:249], v227 offset:12288
	ds_read_b64_tr_b16 v[250:251], v227 offset:14336
	s_waitcnt lgkmcnt(10)
	v_mfma_f32_32x32x16_bf16 v[18:33], v[182:185], v[166:169], v[18:33]
	s_waitcnt lgkmcnt(8)
	v_mfma_f32_32x32x16_bf16 v[2:17], v[222:225], v[166:169], v[2:17]
	s_waitcnt lgkmcnt(6)
	v_mfma_f32_32x32x16_bf16 v[50:65], v[228:231], v[162:165], v[50:65]
	s_waitcnt lgkmcnt(4)
	v_mfma_f32_32x32x16_bf16 v[34:49], v[240:243], v[162:165], v[34:49]
	s_waitcnt lgkmcnt(2)
	v_mfma_f32_32x32x16_bf16 v[18:33], v[244:247], v[162:165], v[18:33]
	s_waitcnt lgkmcnt(0)
	v_mfma_f32_32x32x16_bf16 v[2:17], v[248:251], v[162:165], v[2:17]
	s_setprio 0
	s_and_b64 vcc, exec, s[40:41]
	s_cbranch_vccnz .LBB0_581
; DI void attn_unit(const bf16_t* Q, const bf16_t* Kp, const bf16_t* Vp, bf16_t* O, size_t qrow0, size_t krow0, int ntile, int h, float lam, float lam_init, const float* gsub, LAS unsigned char* lds) {
;     ...
;         if (!shifted) {
;             ps = 0.f;
; #pragma unroll
;             for (int kh = 0; kh < 2; ++kh)
; #pragma unroll
;                 for (int i = 0; i < 16; ++i) { sn[kh][i] = __builtin_amdgcn_exp2f(sn[kh][i]); ps += sn[kh][i]; }
;             l_run += ps;
;         }
	v_exp_f32_e32 v114, v114
	v_exp_f32_e32 v115, v115
	v_exp_f32_e32 v116, v116
	v_exp_f32_e32 v117, v117
	v_add_f32_e32 v1, 0, v114
	v_exp_f32_e32 v118, v118
	v_add_f32_e32 v1, v115, v1
	v_exp_f32_e32 v119, v119
	v_add_f32_e32 v1, v116, v1
	v_exp_f32_e32 v120, v120
	v_add_f32_e32 v1, v117, v1
	v_exp_f32_e32 v121, v121
	v_add_f32_e32 v1, v118, v1
	v_exp_f32_e32 v122, v122
	v_add_f32_e32 v1, v119, v1
	v_exp_f32_e32 v123, v123
	v_add_f32_e32 v1, v120, v1
	v_exp_f32_e32 v124, v124
	v_add_f32_e32 v1, v121, v1
	v_exp_f32_e32 v125, v125
	v_add_f32_e32 v1, v122, v1
	v_exp_f32_e32 v126, v126
	v_add_f32_e32 v1, v123, v1
	v_exp_f32_e32 v127, v127
	v_add_f32_e32 v1, v124, v1
	v_exp_f32_e32 v128, v128
	v_add_f32_e32 v1, v125, v1
	v_exp_f32_e32 v129, v129
	v_add_f32_e32 v1, v126, v1
	v_exp_f32_e32 v130, v130
	v_add_f32_e32 v1, v127, v1
	v_exp_f32_e32 v131, v131
	v_add_f32_e32 v1, v128, v1
	v_exp_f32_e32 v132, v132
	v_add_f32_e32 v1, v129, v1
	v_exp_f32_e32 v133, v133
	v_add_f32_e32 v1, v130, v1
	v_exp_f32_e32 v134, v134
	v_add_f32_e32 v1, v131, v1
	v_exp_f32_e32 v135, v135
	v_add_f32_e32 v1, v132, v1
	v_exp_f32_e32 v136, v136
	v_add_f32_e32 v1, v133, v1
	v_exp_f32_e32 v137, v137
	v_add_f32_e32 v1, v134, v1
	v_exp_f32_e32 v138, v138
	v_add_f32_e32 v1, v135, v1
	v_exp_f32_e32 v139, v139
	v_add_f32_e32 v1, v136, v1
	v_exp_f32_e32 v140, v140
	v_add_f32_e32 v1, v137, v1
	v_exp_f32_e32 v141, v141
	v_add_f32_e32 v1, v138, v1
	v_exp_f32_e32 v142, v142
	v_add_f32_e32 v1, v139, v1
	v_exp_f32_e32 v143, v143
	v_add_f32_e32 v1, v140, v1
	v_exp_f32_e32 v144, v144
	v_add_f32_e32 v1, v141, v1
	v_exp_f32_e32 v145, v145
	v_add_f32_e32 v1, v142, v1
	v_add_f32_e32 v1, v143, v1
	v_add_f32_e32 v1, v144, v1
	v_add_f32_e32 v220, v145, v1
	v_add_f32_e32 v213, v213, v220
